# item loop: exp phase rewritten with packed f32 fma/add (same arithmetic, pairwise row-sum order), PV accumulators in their own registers
# speedup vs baseline: 1.0051x; 1.0051x over previous
.Lit_exp:
	v_cndmask_b32_e64 v35, v219, v208, s[14:15]
	v_sub_f32_e32 v35, v35, v140
	v_cndmask_b32_e64 v142, 1.0, v222, s[16:17]
	v_cndmask_b32_e64 v144, -v140, v35, s[16:17]
	v_pk_fma_f32 v[18:19], v[18:19], v[142:143], v[144:145] op_sel_hi:[1,0,0]
	v_pk_fma_f32 v[20:21], v[20:21], v[142:143], v[144:145] op_sel_hi:[1,0,0]
	v_pk_fma_f32 v[22:23], v[22:23], v[142:143], v[144:145] op_sel_hi:[1,0,0]
	v_pk_fma_f32 v[24:25], v[24:25], v[142:143], v[144:145] op_sel_hi:[1,0,0]
	v_exp_f32_e32 v18, v18
	v_exp_f32_e32 v19, v19
	v_exp_f32_e32 v20, v20
	v_exp_f32_e32 v21, v21
	v_exp_f32_e32 v22, v22
	v_exp_f32_e32 v23, v23
	v_exp_f32_e32 v24, v24
	v_exp_f32_e32 v25, v25
	v_pk_add_f32 v[42:43], v[18:19], v[20:21]
	v_pk_add_f32 v[42:43], v[42:43], v[22:23]
	v_pk_add_f32 v[42:43], v[42:43], v[24:25]
	v_cvt_pk_bf16_f32 v34, v18, v19
	v_cvt_pk_bf16_f32 v35, v20, v21
	v_cvt_pk_bf16_f32 v36, v22, v23
	v_cvt_pk_bf16_f32 v37, v24, v25
	v_pk_fma_f32 v[26:27], v[26:27], v[142:143], v[144:145] op_sel_hi:[1,0,0]
	v_pk_fma_f32 v[28:29], v[28:29], v[142:143], v[144:145] op_sel_hi:[1,0,0]
	v_pk_fma_f32 v[30:31], v[30:31], v[142:143], v[144:145] op_sel_hi:[1,0,0]
	v_pk_fma_f32 v[32:33], v[32:33], v[142:143], v[144:145] op_sel_hi:[1,0,0]
	v_mfma_f32_32x32x16_bf16 v[146:161], v[74:77], v[34:37], 0
	v_mfma_f32_32x32x16_bf16 v[162:177], v[94:97], v[34:37], 0
	v_exp_f32_e32 v26, v26
	v_exp_f32_e32 v27, v27
	v_exp_f32_e32 v28, v28
	v_exp_f32_e32 v29, v29
	v_exp_f32_e32 v30, v30
	v_exp_f32_e32 v31, v31
	v_exp_f32_e32 v32, v32
	v_exp_f32_e32 v33, v33
	v_pk_add_f32 v[42:43], v[42:43], v[26:27]
	v_pk_add_f32 v[42:43], v[42:43], v[28:29]
	v_pk_add_f32 v[42:43], v[42:43], v[30:31]
	v_pk_add_f32 v[42:43], v[42:43], v[32:33]
	v_cvt_pk_bf16_f32 v38, v26, v27
	v_cvt_pk_bf16_f32 v39, v28, v29
	v_cvt_pk_bf16_f32 v40, v30, v31
	v_cvt_pk_bf16_f32 v41, v32, v33
	v_pk_fma_f32 v[2:3], v[2:3], v[142:143], v[144:145] op_sel_hi:[1,0,0]
	v_pk_fma_f32 v[4:5], v[4:5], v[142:143], v[144:145] op_sel_hi:[1,0,0]
	v_pk_fma_f32 v[6:7], v[6:7], v[142:143], v[144:145] op_sel_hi:[1,0,0]
	v_pk_fma_f32 v[8:9], v[8:9], v[142:143], v[144:145] op_sel_hi:[1,0,0]
	v_mfma_f32_32x32x16_bf16 v[146:161], v[70:73], v[38:41], v[146:161]
	v_mfma_f32_32x32x16_bf16 v[162:177], v[102:105], v[38:41], v[162:177]
	v_exp_f32_e32 v2, v2
	v_exp_f32_e32 v3, v3
	v_exp_f32_e32 v4, v4
	v_exp_f32_e32 v5, v5
	v_exp_f32_e32 v6, v6
	v_exp_f32_e32 v7, v7
	v_exp_f32_e32 v8, v8
	v_exp_f32_e32 v9, v9
	v_pk_add_f32 v[42:43], v[42:43], v[2:3]
	v_pk_add_f32 v[42:43], v[42:43], v[4:5]
	v_pk_add_f32 v[42:43], v[42:43], v[6:7]
	v_pk_add_f32 v[42:43], v[42:43], v[8:9]
	v_cvt_pk_bf16_f32 v34, v2, v3
	v_cvt_pk_bf16_f32 v35, v4, v5
	v_cvt_pk_bf16_f32 v36, v6, v7
	v_cvt_pk_bf16_f32 v37, v8, v9
	v_pk_fma_f32 v[10:11], v[10:11], v[142:143], v[144:145] op_sel_hi:[1,0,0]
	v_pk_fma_f32 v[12:13], v[12:13], v[142:143], v[144:145] op_sel_hi:[1,0,0]
	v_pk_fma_f32 v[14:15], v[14:15], v[142:143], v[144:145] op_sel_hi:[1,0,0]
	v_pk_fma_f32 v[16:17], v[16:17], v[142:143], v[144:145] op_sel_hi:[1,0,0]
	v_mfma_f32_32x32x16_bf16 v[146:161], v[86:89], v[34:37], v[146:161]
	v_mfma_f32_32x32x16_bf16 v[162:177], v[106:109], v[34:37], v[162:177]
	v_exp_f32_e32 v10, v10
	v_exp_f32_e32 v11, v11
	v_exp_f32_e32 v12, v12
	v_exp_f32_e32 v13, v13
	v_exp_f32_e32 v14, v14
	v_exp_f32_e32 v15, v15
	v_exp_f32_e32 v16, v16
	v_exp_f32_e32 v17, v17
	v_pk_add_f32 v[42:43], v[42:43], v[10:11]
	v_pk_add_f32 v[42:43], v[42:43], v[12:13]
	v_pk_add_f32 v[42:43], v[42:43], v[14:15]
	v_pk_add_f32 v[42:43], v[42:43], v[16:17]
	v_cvt_pk_bf16_f32 v38, v10, v11
	v_cvt_pk_bf16_f32 v39, v12, v13
	v_cvt_pk_bf16_f32 v40, v14, v15
	v_cvt_pk_bf16_f32 v41, v16, v17
	s_nop 1
	v_mfma_f32_32x32x16_bf16 v[146:161], v[82:85], v[38:41], v[146:161]
	v_mfma_f32_32x32x16_bf16 v[162:177], v[110:113], v[38:41], v[162:177]
	v_add_f32_e32 v44, v42, v43
	v_mov_b32_e32 v2, v44
	s_nop 1
	v_permlane32_swap_b32_e32 v44, v2
	v_add_f32_e32 v2, v44, v2
	s_and_saveexec_b64 s[16:17], s[60:61]
	s_cbranch_execz .Lit_nols
	v_cvt_i32_f32_e32 v3, v2
	v_add_u32_e32 v4, 0x10800, v190
	ds_add_u32 v4, v3

.Lit_noflag:
	s_or_b64 exec, exec, s[16:17]
	s_and_saveexec_b64 s[16:17], s[14:15]
	v_cvt_i32_f32_e32 v3, v146
	v_cvt_i32_f32_e32 v4, v147
	v_cvt_i32_f32_e32 v5, v148
	v_mad_u32_u24 v2, v189, s78, v1
	v_cvt_i32_f32_e32 v6, v149
	ds_add_u32 v2, v3
	ds_add_u32 v2, v4 offset:4
	ds_add_u32 v2, v5 offset:8
	ds_add_u32 v2, v6 offset:12
	v_cvt_i32_f32_e32 v3, v150
	v_cvt_i32_f32_e32 v4, v151
	v_cvt_i32_f32_e32 v5, v152
	v_cvt_i32_f32_e32 v6, v153
	ds_add_u32 v2, v3 offset:32
	ds_add_u32 v2, v4 offset:36
	ds_add_u32 v2, v5 offset:40
	ds_add_u32 v2, v6 offset:44
	v_cvt_i32_f32_e32 v3, v154
	v_cvt_i32_f32_e32 v4, v155
	v_cvt_i32_f32_e32 v5, v156
	v_cvt_i32_f32_e32 v6, v157
	ds_add_u32 v2, v3 offset:64
	ds_add_u32 v2, v4 offset:68
	ds_add_u32 v2, v5 offset:72
	ds_add_u32 v2, v6 offset:76
	v_cvt_i32_f32_e32 v3, v158
	v_cvt_i32_f32_e32 v4, v159
	v_cvt_i32_f32_e32 v5, v160
	v_cvt_i32_f32_e32 v6, v161
	ds_add_u32 v2, v3 offset:96
	ds_add_u32 v2, v4 offset:100
	ds_add_u32 v2, v5 offset:104
	ds_add_u32 v2, v6 offset:108
	v_cvt_i32_f32_e32 v3, v162
	v_cvt_i32_f32_e32 v4, v163
	v_cvt_i32_f32_e32 v5, v164
	v_cvt_i32_f32_e32 v6, v165
	ds_add_u32 v2, v3 offset:128
	ds_add_u32 v2, v4 offset:132
	ds_add_u32 v2, v5 offset:136
	ds_add_u32 v2, v6 offset:140
	v_cvt_i32_f32_e32 v3, v166
	v_cvt_i32_f32_e32 v4, v167
	v_cvt_i32_f32_e32 v5, v168
	v_cvt_i32_f32_e32 v6, v169
	ds_add_u32 v2, v3 offset:160
	ds_add_u32 v2, v4 offset:164
	ds_add_u32 v2, v5 offset:168
	ds_add_u32 v2, v6 offset:172
	v_cvt_i32_f32_e32 v3, v170
	v_cvt_i32_f32_e32 v4, v171
	v_cvt_i32_f32_e32 v5, v172
	v_cvt_i32_f32_e32 v6, v173
	ds_add_u32 v2, v3 offset:192
	ds_add_u32 v2, v4 offset:196
	ds_add_u32 v2, v5 offset:200
	ds_add_u32 v2, v6 offset:204
	v_cvt_i32_f32_e32 v3, v174
	v_cvt_i32_f32_e32 v4, v175
	v_cvt_i32_f32_e32 v5, v176
	v_cvt_i32_f32_e32 v6, v177
	ds_add_u32 v2, v3 offset:224
	ds_add_u32 v2, v4 offset:228
	ds_add_u32 v2, v5 offset:232
	ds_add_u32 v2, v6 offset:236
	s_or_b64 exec, exec, s[16:17]
	s_and_b64 vcc, exec, s[12:13]
	s_cbranch_vccnz .Lit_nov
	s_and_b32 s4, s26, 0xff
	s_lshl_b32 s4, s4, 13
	s_add_u32 s4, s50, s4
	s_addc_u32 s5, s51, 0
	global_load_dwordx4 v[74:77], v194, s[4:5]
	global_load_dwordx4 v[70:73], v194, s[4:5] offset:1024
	global_load_dwordx4 v[86:89], v194, s[4:5] offset:2048
	global_load_dwordx4 v[82:85], v194, s[4:5] offset:3072
	global_load_dwordx4 v[94:97], v200, s[4:5]
	global_load_dwordx4 v[102:105], v202, s[4:5]
	global_load_dwordx4 v[106:109], v204, s[4:5]
	global_load_dwordx4 v[110:113], v206, s[4:5]
